# aligned combo12 with background-conversion start delay 2x32 instead of 2x64
# baseline (speedup 1.0000x reference)
; #define LAS __attribute__((address_space(3)))
; __device__ __forceinline__ void cv_background(Frame& F, const CvPtrs& P, int s) {
;     int tv = threadIdx.x; asm volatile("" : "+v"(tv));
;     const int w = __builtin_amdgcn_readfirstlane(tv >> 6) - 1, lane = tv & 63, nbw = F.G * (NWAVES - 1);
;     LAS float* scr = (LAS float*)(F.lds + RING_OFF + (w + 1) * 16384);
;     const int sh_ = cv_bg_share(s), hi = (sh_ + 1) * CV_BG_PER < CV_BG_TOTAL ? (sh_ + 1) * CV_BG_PER : CV_BG_TOTAL;
;     for (int j = sh_ * CV_BG_PER + F.vcu * (NWAVES - 1) + w; j < hi; j += nbw) {
; __device__ __forceinline__ void xcd_barrier_cv(const XcdBarrier& b, Frame& F, const CvPtrs& P, int s, bool local) {
;     asm volatile("s_waitcnt vmcnt(0)" ::: "memory");
;     __syncthreads();
;     if (threadIdx.x < 64) { if (threadIdx.x == 0) { if (local) xcc_barrier_thread0(b); else xcd_barrier_thread0(b); } }
;     else if (cv_bg_share(s) >= 0 && cv_bg_share(s) < CV_BG_SHARES) cv_background(F, P, s);
.LBB0_769:
	s_and_b64 vcc, exec, s[0:1]
	s_cbranch_vccz .LBB0_1015
	s_sleep 32
	s_sleep 32
	v_mov_b32_e32 v4, v0
	s_mov_b64 s[6:7], -1
	v_readfirstlane_b32 s8, v4
	s_mov_b64 s[0:1], 0
	s_cmp_lt_i32 s89, 5
	s_mov_b64 s[4:5], 0
	s_cbranch_scc1 .LBB0_787
	s_cmp_gt_i32 s89, 7
	s_cbranch_scc0 .LBB0_779
	s_cmp_gt_i32 s89, 8
	s_cbranch_scc0 .LBB0_776
	s_cmp_eq_u32 s89, 9
	s_mov_b64 s[4:5], -1
	s_cbranch_scc0 .LBB0_775
	s_mov_b64 s[4:5], 0
